# mLSTM chunk: the next-chunk prefetch block (conv rows, v piece, gates) moved from the end of the conv segment to just behind the following barrier, where the conv waves have slack
# speedup vs baseline: 1.0170x; 1.0093x over previous
.LBB0_234:
	s_or_b64 exec, exec, s[46:47]
	s_branch .LBB0_245

.LBB0_239:
	s_or_b64 exec, exec, s[60:61]
	v_xor_b32_e32 v0, 0x80000000, v0
	ds_write_b32 v122, v0
	s_or_b64 exec, exec, s[46:47]
	s_branch .LBB0_245
.LBB0_245:
	s_waitcnt lgkmcnt(0)
	s_barrier
	s_cmp_eq_u32 s76, 0x2178000
	s_cbranch_scc1 .Lml_nopf

.Lml_nopf:
	ds_read_b128 v[60:63], v67
	ds_read_b128 v[112:115], v67 offset:16
	ds_read_b128 v[116:119], v67 offset:16384
	ds_read_b128 v[206:209], v67 offset:16400
	v_add_u32_e32 v0, 0x8000, v81
	s_waitcnt lgkmcnt(3)
	v_cvt_pk_bf16_f32 v60, v60, v61
	v_cvt_pk_bf16_f32 v61, v62, v63
	s_waitcnt lgkmcnt(2)
	v_cvt_pk_bf16_f32 v62, v112, v113
	v_cvt_pk_bf16_f32 v63, v114, v115
	ds_write_b128 v69, v[60:63] offset:53248
	s_waitcnt lgkmcnt(2)
	v_cvt_pk_bf16_f32 v60, v116, v117
	v_cvt_pk_bf16_f32 v61, v118, v119
	s_waitcnt lgkmcnt(1)
	v_cvt_pk_bf16_f32 v62, v206, v207
	v_cvt_pk_bf16_f32 v63, v208, v209
	ds_write_b128 v69, v[60:63] offset:62464
	ds_read2_b32 v[2:3], v0 offset1:32
	ds_read_b32 v0, v81 offset:33024
	ds_read_b32 v60, v83 offset:32768
	s_waitcnt lgkmcnt(2)
	v_cvt_pk_bf16_f32 v2, v2, v3
	s_waitcnt lgkmcnt(0)
	v_cvt_pk_bf16_f32 v3, v0, v60
	ds_write_b64 v85, v[2:3]
	s_and_saveexec_b64 s[46:47], s[14:15]
	s_cbranch_execz .LBB0_249
	ds_read_b32 v0, v122
	ds_read_b32 v2, v93
	v_mov_b32_e32 v3, v1
	v_mov_b32_e32 v60, v1
	v_mov_b32_e32 v61, 0xff800000
	s_waitcnt lgkmcnt(1)
	v_add_f32_dpp v0, v0, v0 row_shr:1 row_mask:0xf bank_mask:0xf bound_ctrl:1
	s_nop 1
	v_add_f32_dpp v0, v0, v0 row_shr:2 row_mask:0xf bank_mask:0xf bound_ctrl:1
	s_nop 1
	v_add_f32_dpp v0, v0, v0 row_shr:4 row_mask:0xf bank_mask:0xf bound_ctrl:1
	s_nop 1
	v_add_f32_dpp v0, v0, v0 row_shr:8 row_mask:0xf bank_mask:0xf bound_ctrl:1
	s_nop 1
	v_mov_b32_dpp v3, v0 row_bcast:15 row_mask:0xa bank_mask:0xf
	v_add_f32_e32 v0, v0, v3
	s_nop 1
	v_mov_b32_dpp v60, v0 row_bcast:31 row_mask:0xc bank_mask:0xf
	v_add_f32_e32 v3, v0, v60
	s_waitcnt lgkmcnt(0)
	v_sub_f32_e32 v60, v2, v3
	v_mov_b32_e32 v2, 0xff800000
	s_nop 0
	v_mov_b32_dpp v61, v60 row_shr:1 row_mask:0xf bank_mask:0xf
	v_max_f32_e32 v0, v61, v61
	v_max_f32_e32 v0, v60, v0
	v_add_f32_e32 v61, v203, v3
	s_nop 0
	v_mov_b32_dpp v2, v0 row_shr:2 row_mask:0xf bank_mask:0xf
	v_max_f32_e32 v2, v2, v2
	v_max_f32_e32 v0, v0, v2
	v_mov_b32_e32 v2, 0xff800000
	s_nop 1
	v_mov_b32_dpp v2, v0 row_shr:4 row_mask:0xf bank_mask:0xf
	v_max_f32_e32 v2, v2, v2
	v_max_f32_e32 v0, v0, v2
	v_mov_b32_e32 v2, 0xff800000
	s_nop 1
	v_mov_b32_dpp v2, v0 row_shr:8 row_mask:0xf bank_mask:0xf
	v_max_f32_e32 v2, v2, v2
	v_max_f32_e32 v0, v0, v2
	v_mov_b32_e32 v2, 0xff800000
	s_nop 1
	v_mov_b32_dpp v2, v0 row_bcast:15 row_mask:0xa bank_mask:0xf
	v_max_f32_e32 v2, v2, v2
	v_max_f32_e32 v0, v0, v2
	v_mov_b32_e32 v2, 0xff800000
	s_nop 1
	v_mov_b32_dpp v2, v0 row_bcast:31 row_mask:0xc bank_mask:0xf
	v_max_f32_e32 v2, v2, v2
	v_max_f32_e32 v0, v0, v2
	v_add_f32_e32 v0, v3, v0
	v_max_f32_e32 v62, v61, v0
	v_lshl_or_b32 v0, v168, 2, v174
	ds_bpermute_b32 v2, v0, v3
	ds_bpermute_b32 v0, v0, v62
	v_sub_f32_e32 v3, v3, v62
	ds_write_b32 v123, v3
	v_sub_f32_e32 v3, v61, v62
	v_mul_f32_e32 v3, 0x3fb8aa3b, v3
	s_waitcnt lgkmcnt(1)
	v_sub_f32_e32 v61, v2, v0
	v_add_f32_e32 v61, v60, v61
	v_exp_f32_e32 v3, v3
	v_mul_f32_e32 v61, 0x3fb8aa3b, v61
	v_exp_f32_e32 v61, v61
	v_mul_f32_e32 v62, 0xbfb8aa3b, v62
	v_exp_f32_e32 v62, v62
	ds_write_b32 v124, v60
	ds_write_b32 v125, v3
	ds_write_b32 v126, v61
	ds_write_b32 v127, v62
	s_and_saveexec_b64 s[60:61], s[16:17]
	s_cbranch_execz .LBB0_248
	v_add_f32_e32 v2, v203, v2
	v_sub_f32_e32 v2, v2, v0
	v_mul_f32_e32 v2, 0x3fb8aa3b, v2
	v_exp_f32_e32 v2, v2
	v_mov_b32_e32 v3, s71
	ds_write_b32 v3, v2
